# v070 + the first PV MFMA is issued before the mid-step barrier so the matrix pipe works while the workgroup rendezvous completes
# speedup vs baseline: 1.0093x; 1.0093x over previous
.Lattn_fx_skipw1:
	v_exp_f32_e32 v78, v78
	v_exp_f32_e32 v79, v79
	v_add_f32_e32 v246, v76, v246
	v_add_f32_e32 v246, v77, v246
	v_cvt_pk_bf16_f32 v71, v76, v77
	v_mfma_f32_32x32x16_bf16 v[98:113], v[186:189], v[138:141], v[98:113]
	v_exp_f32_e32 v80, v80
	v_exp_f32_e32 v81, v81
	v_add_f32_e32 v246, v78, v246
	v_add_f32_e32 v246, v79, v246
	v_cvt_pk_bf16_f32 v72, v78, v79
	v_mfma_f32_32x32x16_bf16 v[114:129], v[174:177], v[142:145], v[114:129]
	v_exp_f32_e32 v34, v34
	v_exp_f32_e32 v35, v35
	v_add_f32_e32 v246, v80, v246
	v_add_f32_e32 v246, v81, v246
	v_cvt_pk_bf16_f32 v73, v80, v81
	v_mfma_f32_32x32x16_bf16 v[98:113], v[82:85], v[142:145], v[98:113]
	v_exp_f32_e32 v36, v36
	v_exp_f32_e32 v37, v37
	v_add_f32_e32 v247, v34, v35
	v_cvt_pk_bf16_f32 v74, v34, v35
	s_waitcnt lgkmcnt(0)
	v_mfma_f32_32x32x16_bf16 v[18:33], v[86:89], v[66:69], v[18:33]
	s_barrier
	ds_read_b128 v[162:165], v193 offset:18432
	ds_read_b128 v[178:181], v193 offset:23040
	v_exp_f32_e32 v38, v38
	v_exp_f32_e32 v39, v39
	v_add_f32_e32 v247, v36, v247
	v_add_f32_e32 v247, v37, v247
	v_cvt_pk_bf16_f32 v75, v36, v37
	v_mfma_f32_32x32x16_bf16 v[2:17], v[216:219], v[66:69], v[2:17]
	ds_read_b128 v[166:169], v193 offset:18464
	ds_read_b128 v[182:185], v193 offset:23072
	v_exp_f32_e32 v40, v40
	v_exp_f32_e32 v41, v41
	v_add_f32_e32 v247, v38, v247
	v_add_f32_e32 v247, v39, v247
	v_cvt_pk_bf16_f32 v76, v38, v39
	v_mfma_f32_32x32x16_bf16 v[18:33], v[90:93], v[70:73], v[18:33]
	ds_read_b128 v[170:173], v193 offset:18496
	ds_read_b128 v[186:189], v193 offset:23104
	v_exp_f32_e32 v42, v42
	v_exp_f32_e32 v43, v43
	v_add_f32_e32 v247, v40, v247
	v_add_f32_e32 v247, v41, v247
	v_cvt_pk_bf16_f32 v77, v40, v41
	v_mfma_f32_32x32x16_bf16 v[2:17], v[220:223], v[70:73], v[2:17]
	ds_read_b128 v[174:177], v193 offset:18528
	ds_read_b128 v[82:85], v193 offset:23136
	v_exp_f32_e32 v44, v44
	v_exp_f32_e32 v45, v45
	v_add_f32_e32 v247, v42, v247
	v_add_f32_e32 v247, v43, v247
	v_cvt_pk_bf16_f32 v78, v42, v43
	v_mfma_f32_32x32x16_bf16 v[18:33], v[94:97], v[74:77], v[18:33]
	v_exp_f32_e32 v46, v46
	v_exp_f32_e32 v47, v47
	v_add_f32_e32 v247, v44, v247
	v_add_f32_e32 v247, v45, v247
	v_cvt_pk_bf16_f32 v79, v44, v45
	v_mfma_f32_32x32x16_bf16 v[2:17], v[224:227], v[74:77], v[2:17]
	v_exp_f32_e32 v48, v48
	v_exp_f32_e32 v49, v49
	v_add_f32_e32 v247, v46, v247
	v_add_f32_e32 v247, v47, v247
	v_cvt_pk_bf16_f32 v80, v46, v47
	v_cvt_pk_bf16_f32 v81, v48, v49
	v_add_f32_e32 v247, v48, v247
	v_add_f32_e32 v247, v49, v247
	v_mfma_f32_32x32x16_bf16 v[18:33], v[212:215], v[78:81], v[18:33]
	v_mfma_f32_32x32x16_bf16 v[2:17], v[242:245], v[78:81], v[2:17]
	v_add_f32_e32 v210, v210, v246
	v_add_f32_e32 v210, v210, v247
	s_min_i32 s24, s10, s58
	s_mul_i32 s44, s24, 0xa0000
	s_add_u32 s44, s3, s44
	s_addc_u32 s45, s12, 0
	s_lshl_b32 s46, s24, 7
	s_add_u32 s46, s15, s46
	s_addc_u32 s47, s23, 0
	global_load_dwordx4 v[146:149], v252, s[44:45] offset:1024
	global_load_dwordx4 v[150:153], v253, s[46:47]
	v_exp_f32_e32 v114, v114
	v_exp_f32_e32 v115, v115
	v_exp_f32_e32 v116, v116
	v_exp_f32_e32 v117, v117
	v_add_f32_e32 v246, v114, v115
	v_cvt_pk_bf16_f32 v114, v114, v115
	s_waitcnt lgkmcnt(0)
	v_mfma_f32_32x32x16_bf16 v[66:81], v[162:165], v[130:133], v[50:65]
	ds_read_b128 v[86:89], v248
	ds_read_b128 v[216:219], v248 offset:4608
	v_exp_f32_e32 v118, v118
	v_exp_f32_e32 v119, v119
	v_add_f32_e32 v246, v116, v246
	v_add_f32_e32 v246, v117, v246
	v_cvt_pk_bf16_f32 v115, v116, v117
	v_mfma_f32_32x32x16_bf16 v[34:49], v[178:181], v[130:133], v[50:65]
	ds_read_b128 v[90:93], v248 offset:32
	ds_read_b128 v[220:223], v248 offset:4640
	v_exp_f32_e32 v120, v120
	v_exp_f32_e32 v121, v121
	v_add_f32_e32 v246, v118, v246
	v_add_f32_e32 v246, v119, v246
	v_cvt_pk_bf16_f32 v116, v118, v119
	v_mfma_f32_32x32x16_bf16 v[66:81], v[166:169], v[134:137], v[66:81]
	ds_read_b128 v[94:97], v248 offset:64
	ds_read_b128 v[224:227], v248 offset:4672
	v_exp_f32_e32 v122, v122
	v_exp_f32_e32 v123, v123
	v_add_f32_e32 v246, v120, v246
	v_add_f32_e32 v246, v121, v246
	v_cvt_pk_bf16_f32 v117, v120, v121
	v_mfma_f32_32x32x16_bf16 v[34:49], v[182:185], v[134:137], v[34:49]
	ds_read_b128 v[212:215], v248 offset:96
	ds_read_b128 v[242:245], v248 offset:4704
	v_exp_f32_e32 v124, v124
	v_exp_f32_e32 v125, v125
	v_add_f32_e32 v246, v122, v246
	v_add_f32_e32 v246, v123, v246
	v_cvt_pk_bf16_f32 v118, v122, v123
	v_mfma_f32_32x32x16_bf16 v[66:81], v[170:173], v[138:141], v[66:81]
	s_cmp_ge_u32 s11, s16
	s_cbranch_scc1 .Lattn_fx_skipw2
	s_waitcnt vmcnt(2)
	ds_write_b128 v192, v[154:157] offset:55296
	ds_write_b128 v204, v[158:161] offset:64512
.Lattn_fx_skipw2:
	v_exp_f32_e32 v126, v126
	v_exp_f32_e32 v127, v127
	v_add_f32_e32 v246, v124, v246
	v_add_f32_e32 v246, v125, v246
	v_cvt_pk_bf16_f32 v119, v124, v125
	v_mfma_f32_32x32x16_bf16 v[34:49], v[186:189], v[138:141], v[34:49]
	v_exp_f32_e32 v128, v128
	v_exp_f32_e32 v129, v129
	v_add_f32_e32 v246, v126, v246
	v_add_f32_e32 v246, v127, v246
	v_cvt_pk_bf16_f32 v120, v126, v127
	v_mfma_f32_32x32x16_bf16 v[66:81], v[174:177], v[142:145], v[66:81]
	v_exp_f32_e32 v98, v98
	v_exp_f32_e32 v99, v99
	v_add_f32_e32 v246, v128, v246
	v_add_f32_e32 v246, v129, v246
	v_cvt_pk_bf16_f32 v121, v128, v129
	v_mfma_f32_32x32x16_bf16 v[34:49], v[82:85], v[142:145], v[34:49]
	v_exp_f32_e32 v100, v100
	v_exp_f32_e32 v101, v101
	v_add_f32_e32 v247, v98, v99
	v_cvt_pk_bf16_f32 v122, v98, v99
	s_waitcnt lgkmcnt(0)
	v_mfma_f32_32x32x16_bf16 v[18:33], v[86:89], v[114:117], v[18:33]
	s_barrier
	ds_read_b128 v[162:165], v193 offset:55296
	ds_read_b128 v[178:181], v193 offset:59904
	v_exp_f32_e32 v102, v102
	v_exp_f32_e32 v103, v103
	v_add_f32_e32 v247, v100, v247
	v_add_f32_e32 v247, v101, v247
	v_cvt_pk_bf16_f32 v123, v100, v101
	v_mfma_f32_32x32x16_bf16 v[2:17], v[216:219], v[114:117], v[2:17]
	ds_read_b128 v[166:169], v193 offset:55328
	ds_read_b128 v[182:185], v193 offset:59936
	v_exp_f32_e32 v104, v104
	v_exp_f32_e32 v105, v105
	v_add_f32_e32 v247, v102, v247
	v_add_f32_e32 v247, v103, v247
	v_cvt_pk_bf16_f32 v124, v102, v103
	v_mfma_f32_32x32x16_bf16 v[18:33], v[90:93], v[118:121], v[18:33]
	ds_read_b128 v[170:173], v193 offset:55360
	ds_read_b128 v[186:189], v193 offset:59968
	v_exp_f32_e32 v106, v106
	v_exp_f32_e32 v107, v107
	v_add_f32_e32 v247, v104, v247
	v_add_f32_e32 v247, v105, v247
	v_cvt_pk_bf16_f32 v125, v104, v105
	v_mfma_f32_32x32x16_bf16 v[2:17], v[220:223], v[118:121], v[2:17]
	ds_read_b128 v[174:177], v193 offset:55392
	ds_read_b128 v[82:85], v193 offset:60000
	v_exp_f32_e32 v108, v108
	v_exp_f32_e32 v109, v109
	v_add_f32_e32 v247, v106, v247
	v_add_f32_e32 v247, v107, v247
	v_cvt_pk_bf16_f32 v126, v106, v107
	v_mfma_f32_32x32x16_bf16 v[18:33], v[94:97], v[122:125], v[18:33]
	v_exp_f32_e32 v110, v110
	v_exp_f32_e32 v111, v111
	v_add_f32_e32 v247, v108, v247
	v_add_f32_e32 v247, v109, v247
	v_cvt_pk_bf16_f32 v127, v108, v109
	v_mfma_f32_32x32x16_bf16 v[2:17], v[224:227], v[122:125], v[2:17]
	v_exp_f32_e32 v112, v112
	v_exp_f32_e32 v113, v113
	v_add_f32_e32 v247, v110, v247
	v_add_f32_e32 v247, v111, v247
	v_cvt_pk_bf16_f32 v128, v110, v111
	v_cvt_pk_bf16_f32 v129, v112, v113
	v_add_f32_e32 v247, v112, v247
	v_add_f32_e32 v247, v113, v247
	v_mfma_f32_32x32x16_bf16 v[18:33], v[212:215], v[126:129], v[18:33]
	v_mfma_f32_32x32x16_bf16 v[2:17], v[242:245], v[126:129], v[2:17]
	v_add_f32_e32 v210, v210, v246
	v_add_f32_e32 v210, v210, v247
	s_add_i32 s10, s10, 2
	s_cmp_lt_u32 s11, s16
	s_cbranch_scc0 .Lattn_fx_exit0
	s_add_i32 s11, s10, -1
	s_min_i32 s1, s11, s58
	s_mul_i32 s44, s1, 0xa0000
	s_add_u32 s44, s3, s44
	s_addc_u32 s45, s12, 0
	s_lshl_b32 s46, s1, 7
	s_add_u32 s46, s15, s46
	s_addc_u32 s47, s23, 0
	s_add_i32 s24, s10, -2
	s_cmp_lt_u32 s24, s16
	s_cselect_b64 s[0:1], -1, 0
	global_load_dwordx4 v[154:157], v252, s[44:45] offset:1024
	global_load_dwordx4 v[158:161], v253, s[46:47]
	v_exp_f32_e32 v66, v66
	v_exp_f32_e32 v67, v67
	v_exp_f32_e32 v68, v68
	v_exp_f32_e32 v69, v69
	v_add_f32_e32 v246, v66, v67
	v_cvt_pk_bf16_f32 v66, v66, v67
	s_waitcnt lgkmcnt(0)
	v_mfma_f32_32x32x16_bf16 v[114:129], v[162:165], v[130:133], v[50:65]
	ds_read_b128 v[86:89], v248 offset:18432
	ds_read_b128 v[216:219], v248 offset:23040
	v_exp_f32_e32 v70, v70
	v_exp_f32_e32 v71, v71
	v_add_f32_e32 v246, v68, v246
	v_add_f32_e32 v246, v69, v246
	v_cvt_pk_bf16_f32 v67, v68, v69
	v_mfma_f32_32x32x16_bf16 v[98:113], v[178:181], v[130:133], v[50:65]
	ds_read_b128 v[90:93], v248 offset:18464
	ds_read_b128 v[220:223], v248 offset:23072
	v_exp_f32_e32 v72, v72
	v_exp_f32_e32 v73, v73
	v_add_f32_e32 v246, v70, v246
	v_add_f32_e32 v246, v71, v246
	v_cvt_pk_bf16_f32 v68, v70, v71
	v_mfma_f32_32x32x16_bf16 v[114:129], v[166:169], v[134:137], v[114:129]
	ds_read_b128 v[94:97], v248 offset:18496
	ds_read_b128 v[224:227], v248 offset:23104
	v_exp_f32_e32 v74, v74
	v_exp_f32_e32 v75, v75
	v_add_f32_e32 v246, v72, v246
	v_add_f32_e32 v246, v73, v246
	v_cvt_pk_bf16_f32 v69, v72, v73
	v_mfma_f32_32x32x16_bf16 v[98:113], v[182:185], v[134:137], v[98:113]
	ds_read_b128 v[212:215], v248 offset:18528
	ds_read_b128 v[242:245], v248 offset:23136
	v_exp_f32_e32 v76, v76
	v_exp_f32_e32 v77, v77
	v_add_f32_e32 v246, v74, v246
	v_add_f32_e32 v246, v75, v246
	v_cvt_pk_bf16_f32 v70, v74, v75
	v_mfma_f32_32x32x16_bf16 v[114:129], v[170:173], v[138:141], v[114:129]
	s_cmp_ge_u32 s24, s16
	s_cbranch_scc1 .Lattn_fx_skipw3
	s_waitcnt vmcnt(2)
	ds_write_b128 v192, v[146:149] offset:36864
	ds_write_b128 v204, v[150:153] offset:46080
.Lattn_fx_skipw3:
	v_exp_f32_e32 v78, v78
	v_exp_f32_e32 v79, v79
	v_add_f32_e32 v246, v76, v246
	v_add_f32_e32 v246, v77, v246
	v_cvt_pk_bf16_f32 v71, v76, v77
	v_mfma_f32_32x32x16_bf16 v[98:113], v[186:189], v[138:141], v[98:113]
	v_exp_f32_e32 v80, v80
	v_exp_f32_e32 v81, v81
	v_add_f32_e32 v246, v78, v246
	v_add_f32_e32 v246, v79, v246
	v_cvt_pk_bf16_f32 v72, v78, v79
	v_mfma_f32_32x32x16_bf16 v[114:129], v[174:177], v[142:145], v[114:129]
	v_exp_f32_e32 v34, v34
	v_exp_f32_e32 v35, v35
	v_add_f32_e32 v246, v80, v246
	v_add_f32_e32 v246, v81, v246
	v_cvt_pk_bf16_f32 v73, v80, v81
	v_mfma_f32_32x32x16_bf16 v[98:113], v[82:85], v[142:145], v[98:113]
	v_exp_f32_e32 v36, v36
	v_exp_f32_e32 v37, v37
	v_add_f32_e32 v247, v34, v35
	v_cvt_pk_bf16_f32 v74, v34, v35
	s_waitcnt lgkmcnt(0)
	v_mfma_f32_32x32x16_bf16 v[18:33], v[86:89], v[66:69], v[18:33]
	s_barrier
	ds_read_b128 v[162:165], v193 offset:36864
	ds_read_b128 v[178:181], v193 offset:41472
	v_exp_f32_e32 v38, v38
	v_exp_f32_e32 v39, v39
	v_add_f32_e32 v247, v36, v247
	v_add_f32_e32 v247, v37, v247
	v_cvt_pk_bf16_f32 v75, v36, v37
	v_mfma_f32_32x32x16_bf16 v[2:17], v[216:219], v[66:69], v[2:17]
	ds_read_b128 v[166:169], v193 offset:36896
	ds_read_b128 v[182:185], v193 offset:41504
	v_exp_f32_e32 v40, v40
	v_exp_f32_e32 v41, v41
	v_add_f32_e32 v247, v38, v247
	v_add_f32_e32 v247, v39, v247
	v_cvt_pk_bf16_f32 v76, v38, v39
	v_mfma_f32_32x32x16_bf16 v[18:33], v[90:93], v[70:73], v[18:33]
	ds_read_b128 v[170:173], v193 offset:36928
	ds_read_b128 v[186:189], v193 offset:41536
	v_exp_f32_e32 v42, v42
	v_exp_f32_e32 v43, v43
	v_add_f32_e32 v247, v40, v247
	v_add_f32_e32 v247, v41, v247
	v_cvt_pk_bf16_f32 v77, v40, v41
	v_mfma_f32_32x32x16_bf16 v[2:17], v[220:223], v[70:73], v[2:17]
	ds_read_b128 v[174:177], v193 offset:36960
	ds_read_b128 v[82:85], v193 offset:41568
	v_exp_f32_e32 v44, v44
	v_exp_f32_e32 v45, v45
	v_add_f32_e32 v247, v42, v247
	v_add_f32_e32 v247, v43, v247
	v_cvt_pk_bf16_f32 v78, v42, v43
	v_mfma_f32_32x32x16_bf16 v[18:33], v[94:97], v[74:77], v[18:33]
	v_exp_f32_e32 v46, v46
	v_exp_f32_e32 v47, v47
	v_add_f32_e32 v247, v44, v247
	v_add_f32_e32 v247, v45, v247
	v_cvt_pk_bf16_f32 v79, v44, v45
	v_mfma_f32_32x32x16_bf16 v[2:17], v[224:227], v[74:77], v[2:17]
	v_exp_f32_e32 v48, v48
	v_exp_f32_e32 v49, v49
	v_add_f32_e32 v247, v46, v247
	v_add_f32_e32 v247, v47, v247
	v_cvt_pk_bf16_f32 v80, v46, v47
	v_cvt_pk_bf16_f32 v81, v48, v49
	v_add_f32_e32 v247, v48, v247
	v_add_f32_e32 v247, v49, v247
	v_mfma_f32_32x32x16_bf16 v[18:33], v[212:215], v[78:81], v[18:33]
	v_mfma_f32_32x32x16_bf16 v[2:17], v[242:245], v[78:81], v[2:17]
	v_add_f32_e32 v210, v210, v246
	v_add_f32_e32 v210, v210, v247
	s_min_i32 s24, s10, s58
	s_mul_i32 s44, s24, 0xa0000
	s_add_u32 s44, s3, s44
	s_addc_u32 s45, s12, 0
	s_lshl_b32 s46, s24, 7
	s_add_u32 s46, s15, s46
	s_addc_u32 s47, s23, 0
	global_load_dwordx4 v[146:149], v252, s[44:45] offset:1024
	global_load_dwordx4 v[150:153], v253, s[46:47]
	v_exp_f32_e32 v114, v114
	v_exp_f32_e32 v115, v115
	v_exp_f32_e32 v116, v116
	v_exp_f32_e32 v117, v117
	v_add_f32_e32 v246, v114, v115
	v_cvt_pk_bf16_f32 v114, v114, v115
	s_waitcnt lgkmcnt(0)
	v_mfma_f32_32x32x16_bf16 v[66:81], v[162:165], v[130:133], v[50:65]
	ds_read_b128 v[86:89], v248 offset:55296
	ds_read_b128 v[216:219], v248 offset:59904
	v_exp_f32_e32 v118, v118
	v_exp_f32_e32 v119, v119
	v_add_f32_e32 v246, v116, v246
	v_add_f32_e32 v246, v117, v246
	v_cvt_pk_bf16_f32 v115, v116, v117
	v_mfma_f32_32x32x16_bf16 v[34:49], v[178:181], v[130:133], v[50:65]
	ds_read_b128 v[90:93], v248 offset:55328
	ds_read_b128 v[220:223], v248 offset:59936
	v_exp_f32_e32 v120, v120
	v_exp_f32_e32 v121, v121
	v_add_f32_e32 v246, v118, v246
	v_add_f32_e32 v246, v119, v246
	v_cvt_pk_bf16_f32 v116, v118, v119
	v_mfma_f32_32x32x16_bf16 v[66:81], v[166:169], v[134:137], v[66:81]
	ds_read_b128 v[94:97], v248 offset:55360
	ds_read_b128 v[224:227], v248 offset:59968
	v_exp_f32_e32 v122, v122
	v_exp_f32_e32 v123, v123
	v_add_f32_e32 v246, v120, v246
	v_add_f32_e32 v246, v121, v246
	v_cvt_pk_bf16_f32 v117, v120, v121
	v_mfma_f32_32x32x16_bf16 v[34:49], v[182:185], v[134:137], v[34:49]
	ds_read_b128 v[212:215], v248 offset:55392
	ds_read_b128 v[242:245], v248 offset:60000
	v_exp_f32_e32 v124, v124
	v_exp_f32_e32 v125, v125
	v_add_f32_e32 v246, v122, v246
	v_add_f32_e32 v246, v123, v246
	v_cvt_pk_bf16_f32 v118, v122, v123
	v_mfma_f32_32x32x16_bf16 v[66:81], v[170:173], v[138:141], v[66:81]
	s_cmp_ge_u32 s11, s16
	s_cbranch_scc1 .Lattn_fx_skipw4
	s_waitcnt vmcnt(2)
	ds_write_b128 v192, v[154:157]
	ds_write_b128 v204, v[158:161] offset:9216
; template <int HD, int MODE> ...
;     ...
;     int t = t0;
;     for (; t + 1 < t1; t += 2) { ATT_STEP(sa0, sa1, sb0, sb1, t, kstB, vstB, kstA, vstA); ATT_STEP(sb0, sb1, sa0, sa1, t + 1, kstA, vstA, kstB, vstB); }
.Lattn_fx_skipw4:
	v_exp_f32_e32 v126, v126
	v_exp_f32_e32 v127, v127
	v_add_f32_e32 v246, v124, v246
	v_add_f32_e32 v246, v125, v246
	v_cvt_pk_bf16_f32 v119, v124, v125
	v_mfma_f32_32x32x16_bf16 v[34:49], v[186:189], v[138:141], v[34:49]
	v_exp_f32_e32 v128, v128
	v_exp_f32_e32 v129, v129
	v_add_f32_e32 v246, v126, v246
	v_add_f32_e32 v246, v127, v246
	v_cvt_pk_bf16_f32 v120, v126, v127
	v_mfma_f32_32x32x16_bf16 v[66:81], v[174:177], v[142:145], v[66:81]
	v_exp_f32_e32 v98, v98
	v_exp_f32_e32 v99, v99
	v_add_f32_e32 v246, v128, v246
	v_add_f32_e32 v246, v129, v246
	v_cvt_pk_bf16_f32 v121, v128, v129
	v_mfma_f32_32x32x16_bf16 v[34:49], v[82:85], v[142:145], v[34:49]
	v_exp_f32_e32 v100, v100
	v_exp_f32_e32 v101, v101
	v_add_f32_e32 v247, v98, v99
	v_cvt_pk_bf16_f32 v122, v98, v99
	s_waitcnt lgkmcnt(0)
	v_mfma_f32_32x32x16_bf16 v[18:33], v[86:89], v[114:117], v[18:33]
	s_barrier
	ds_read_b128 v[162:165], v193
	ds_read_b128 v[178:181], v193 offset:4608
	v_exp_f32_e32 v102, v102
	v_exp_f32_e32 v103, v103
	v_add_f32_e32 v247, v100, v247
	v_add_f32_e32 v247, v101, v247
	v_cvt_pk_bf16_f32 v123, v100, v101
	v_mfma_f32_32x32x16_bf16 v[2:17], v[216:219], v[114:117], v[2:17]
	ds_read_b128 v[166:169], v193 offset:32
	ds_read_b128 v[182:185], v193 offset:4640
	v_exp_f32_e32 v104, v104
	v_exp_f32_e32 v105, v105
	v_add_f32_e32 v247, v102, v247
	v_add_f32_e32 v247, v103, v247
	v_cvt_pk_bf16_f32 v124, v102, v103
	v_mfma_f32_32x32x16_bf16 v[18:33], v[90:93], v[118:121], v[18:33]
	ds_read_b128 v[170:173], v193 offset:64
	ds_read_b128 v[186:189], v193 offset:4672
	v_exp_f32_e32 v106, v106
	v_exp_f32_e32 v107, v107
	v_add_f32_e32 v247, v104, v247
	v_add_f32_e32 v247, v105, v247
	v_cvt_pk_bf16_f32 v125, v104, v105
	v_mfma_f32_32x32x16_bf16 v[2:17], v[220:223], v[118:121], v[2:17]
	ds_read_b128 v[174:177], v193 offset:96
	ds_read_b128 v[82:85], v193 offset:4704
	v_exp_f32_e32 v108, v108
	v_exp_f32_e32 v109, v109
	v_add_f32_e32 v247, v106, v247
	v_add_f32_e32 v247, v107, v247
	v_cvt_pk_bf16_f32 v126, v106, v107
	v_mfma_f32_32x32x16_bf16 v[18:33], v[94:97], v[122:125], v[18:33]
	v_exp_f32_e32 v110, v110
	v_exp_f32_e32 v111, v111
	v_add_f32_e32 v247, v108, v247
	v_add_f32_e32 v247, v109, v247
	v_cvt_pk_bf16_f32 v127, v108, v109
	v_mfma_f32_32x32x16_bf16 v[2:17], v[224:227], v[122:125], v[2:17]
	v_exp_f32_e32 v112, v112
	v_exp_f32_e32 v113, v113
	v_add_f32_e32 v247, v110, v247
	v_add_f32_e32 v247, v111, v247
	v_cvt_pk_bf16_f32 v128, v110, v111
	v_cvt_pk_bf16_f32 v129, v112, v113
	v_add_f32_e32 v247, v112, v247
	v_add_f32_e32 v247, v113, v247
	v_mfma_f32_32x32x16_bf16 v[18:33], v[212:215], v[126:129], v[18:33]
	v_mfma_f32_32x32x16_bf16 v[2:17], v[242:245], v[126:129], v[2:17]
	v_add_f32_e32 v210, v210, v246
	v_add_f32_e32 v210, v210, v247
	s_add_i32 s10, s10, 2
	s_cmp_lt_u32 s11, s16
	s_cbranch_scc0 .Lattn_fx_exit1
	s_branch .Lattn_fx_top
